# stack: DSA loop tweaks (pitch 320, deep LDS and global prefetch), IDX score loop fragment reads up front and load-only wait, write-through stores for mixer outputs
# speedup vs baseline: 1.0002x; 1.0002x over previous
; #define LAS __attribute__((address_space(3)))
; #define LDS_WAIT() asm volatile("s_waitcnt lgkmcnt(0)" ::: "memory")
; __device__ __forceinline__ void idx_unit(bf16* QB, float* SC, int* SEL, const float* qg, const float* kg, int b, int tp, LAS unsigned char* wl, int lane, bool do_norm) {
;     ...
;         for (int s0 = 0; s0 < ce; s0 += 64) {
; #pragma unroll
;             for (int i = 0; i < 8; ++i) *(LAS bf16x8*)(sdst + (8 * i) * 144) = cur[i];
;             const int sn = (s0 + 64 < ce) ? s0 + 64 : 0;
; #pragma unroll
;             for (int i = 0; i < 8; ++i) cur[i] = *(const bf16x8*)(kg8 + (size_t)(sn + 8 * i) * NBP);
;             LDS_WAIT();
; #pragma unroll
;             for (int tt = 0; tt < 2; ++tt) {
;                 f32x16 acc0, acc1;
; #pragma unroll
;                 for (int r = 0; r < 16; ++r) { acc0[r] = 0.f; acc1[r] = 0.f; }
; #pragma unroll
;                 for (int ks = 0; ks < 4; ++ks) { const bf16x8 bfr = *(const LAS bf16x8*)(fsrc + tt * 32 * 144 + 32 * ks);
;                     acc0 = __builtin_amdgcn_mfma_f32_32x32x16_bf16(af[0][ks], bfr, acc0, 0, 0, 0); acc1 = __builtin_amdgcn_mfma_f32_32x32x16_bf16(af[1][ks], bfr, acc1, 0, 0, 0); }
;                 float pa = 0.f, pb = 0.f, pc = 0.f, pd = 0.f;
; #pragma unroll
;                 for (int r = 0; r < 8; ++r) { pa += w[0][r] * (__builtin_fmaxf(acc0[r], 0.f) * 0.125f); pb += w[1][r] * (__builtin_fmaxf(acc0[8 + r], 0.f) * 0.125f);
;                                               pc += w[2][r] * (__builtin_fmaxf(acc1[r], 0.f) * 0.125f); pd += w[3][r] * (__builtin_fmaxf(acc1[8 + r], 0.f) * 0.125f); }
;                 const float snd0 = hi ? pa : pb, snd1 = hi ? pc : pd; const float rcv0 = __shfl_xor(snd0, 32), rcv1 = __shfl_xor(snd1, 32);
;                 scw0[s0 + 32 * tt] = (hi ? pb : pa) + rcv0;
;                 scw1[s0 + 32 * tt] = (hi ? pd : pc) + rcv1;
;             }
.LBB0_243:
	s_add_i32 s3, s0, 64
	s_cmp_lt_i32 s0, s7
	s_cselect_b64 s[0:1], -1, 0
	s_and_b64 vcc, s[0:1], exec
	s_cselect_b32 s4, s3, 0
	v_mad_u64_u32 v[0:1], s[0:1], s4, v212, v[132:133]
	s_waitcnt vmcnt(4)
	ds_write_b128 v101, v[64:67]
	ds_write_b128 v101, v[72:75] offset:1152
	ds_write_b128 v101, v[68:71] offset:2304
	ds_write_b128 v101, v[80:83] offset:3456
	ds_write_b128 v101, v[76:79] offset:4608
	ds_write_b128 v101, v[88:91] offset:5760
	ds_write_b128 v101, v[84:87] offset:6912
	ds_write_b128 v101, v[92:95] offset:8064
	s_or_b32 s0, s4, 8
	global_load_dwordx4 v[64:67], v[0:1], off
	v_mad_u64_u32 v[0:1], s[0:1], s0, v212, v[132:133]
	s_or_b32 s0, s4, 16
	global_load_dwordx4 v[72:75], v[0:1], off
	v_mad_u64_u32 v[0:1], s[0:1], s0, v212, v[132:133]
	s_or_b32 s0, s4, 24
	global_load_dwordx4 v[68:71], v[0:1], off
	v_mad_u64_u32 v[0:1], s[0:1], s0, v212, v[132:133]
	s_or_b32 s0, s4, 32
	global_load_dwordx4 v[80:83], v[0:1], off
	v_mad_u64_u32 v[0:1], s[0:1], s0, v212, v[132:133]
	s_or_b32 s0, s4, 40
	global_load_dwordx4 v[76:79], v[0:1], off
	v_mad_u64_u32 v[0:1], s[0:1], s0, v212, v[132:133]
	s_or_b32 s0, s4, 48
	global_load_dwordx4 v[88:91], v[0:1], off
	v_mad_u64_u32 v[0:1], s[0:1], s0, v212, v[132:133]
	s_or_b32 s0, s4, 56
	global_load_dwordx4 v[84:87], v[0:1], off
	v_mad_u64_u32 v[0:1], s[0:1], s0, v212, v[132:133]
	global_load_dwordx4 v[92:95], v[0:1], off
	s_waitcnt lgkmcnt(0)
	ds_read_b128 v[138:141], v103
	ds_read_b128 v[142:145], v103 offset:32
	ds_read_b128 v[146:149], v103 offset:64
	ds_read_b128 v[150:153], v103 offset:96
	s_waitcnt lgkmcnt(3)
	v_mfma_f32_32x32x16_bf16 v[16:31], v[40:43], v[138:141], 0
	v_add_co_u32_e64 v136, s[0:1], s5, v134
	s_nop 1
	v_addc_co_u32_e64 v137, s[0:1], 0, v135, s[0:1]
	s_mov_b64 s[0:1], 0x100
	v_mfma_f32_32x32x16_bf16 v[0:15], v[56:59], v[138:141], 0
	s_waitcnt lgkmcnt(2)
	v_mfma_f32_32x32x16_bf16 v[0:15], v[48:51], v[142:145], v[0:15]
	v_mfma_f32_32x32x16_bf16 v[16:31], v[32:35], v[142:145], v[16:31]
	s_waitcnt lgkmcnt(1)
	v_mfma_f32_32x32x16_bf16 v[0:15], v[52:55], v[146:149], v[0:15]
	v_mfma_f32_32x32x16_bf16 v[16:31], v[36:39], v[146:149], v[16:31]
	s_waitcnt lgkmcnt(0)
	v_mfma_f32_32x32x16_bf16 v[0:15], v[60:63], v[150:153], v[0:15]
	v_mfma_f32_32x32x16_bf16 v[16:31], v[44:47], v[150:153], v[16:31]
	ds_read_b128 v[154:157], v103 offset:4608
	ds_read_b128 v[158:161], v103 offset:4640
	ds_read_b128 v[162:165], v103 offset:4672
	ds_read_b128 v[166:169], v103 offset:4704
	s_nop 10
	v_max_f32_e32 v0, v0, v0
	v_max_f32_e32 v0, 0, v0
	v_max_f32_e32 v1, v1, v1
	v_mul_f32_e32 v0, 0x3e000000, v0
	v_max_f32_e32 v1, 0, v1
	v_fma_f32 v0, v232, v0, 0
	v_max_f32_e32 v8, v8, v8
	v_mul_f32_e32 v1, 0x3e000000, v1
	v_max_f32_e32 v8, 0, v8
	v_fmac_f32_e32 v0, v233, v1
	v_max_f32_e32 v1, v9, v9
	v_max_f32_e32 v16, v16, v16
	v_mul_f32_e32 v8, 0x3e000000, v8
	v_max_f32_e32 v1, 0, v1
	v_max_f32_e32 v16, 0, v16
	v_fma_f32 v8, v240, v8, 0
	v_max_f32_e32 v17, v17, v17
	v_mul_f32_e32 v1, 0x3e000000, v1
	v_mul_f32_e32 v16, 0x3e000000, v16
	v_max_f32_e32 v17, 0, v17
	v_fmac_f32_e32 v8, v241, v1
	v_max_f32_e32 v1, v18, v18
	v_fma_f32 v16, v131, v16, 0
	v_max_f32_e32 v24, v24, v24
	v_mul_f32_e32 v17, 0x3e000000, v17
	v_max_f32_e32 v1, 0, v1
	v_max_f32_e32 v24, 0, v24
	v_fmac_f32_e32 v16, v217, v17
	v_max_f32_e32 v17, v25, v25
	v_mul_f32_e32 v1, 0x3e000000, v1
	v_mul_f32_e32 v24, 0x3e000000, v24
	v_max_f32_e32 v17, 0, v17
	v_fmac_f32_e32 v16, v218, v1
	v_max_f32_e32 v1, v26, v26
	v_fma_f32 v24, v224, v24, 0
	v_mul_f32_e32 v17, 0x3e000000, v17
	v_max_f32_e32 v1, 0, v1
	v_fmac_f32_e32 v24, v225, v17
	v_mul_f32_e32 v1, 0x3e000000, v1
	v_fmac_f32_e32 v24, v226, v1
	v_max_f32_e32 v1, v2, v2
	v_max_f32_e32 v1, 0, v1
	v_mul_f32_e32 v1, 0x3e000000, v1
	v_fmac_f32_e32 v0, v234, v1
	v_max_f32_e32 v1, v10, v10
	v_max_f32_e32 v1, 0, v1
	v_mul_f32_e32 v1, 0x3e000000, v1
	v_fmac_f32_e32 v8, v242, v1
	v_max_f32_e32 v1, v19, v19
	v_max_f32_e32 v1, 0, v1
	v_mul_f32_e32 v1, 0x3e000000, v1
	v_fmac_f32_e32 v16, v219, v1
	v_max_f32_e32 v1, v27, v27
	v_max_f32_e32 v1, 0, v1
	v_mul_f32_e32 v1, 0x3e000000, v1
	v_fmac_f32_e32 v24, v227, v1
	v_max_f32_e32 v1, v3, v3
	v_max_f32_e32 v1, 0, v1
	v_mul_f32_e32 v1, 0x3e000000, v1
	v_fmac_f32_e32 v0, v235, v1
	v_max_f32_e32 v1, v11, v11
	v_max_f32_e32 v1, 0, v1
	v_mul_f32_e32 v1, 0x3e000000, v1
	v_fmac_f32_e32 v8, v243, v1
	v_max_f32_e32 v1, v20, v20
	v_max_f32_e32 v1, 0, v1
	v_mul_f32_e32 v1, 0x3e000000, v1
	v_fmac_f32_e32 v16, v220, v1
	v_max_f32_e32 v1, v28, v28
	v_max_f32_e32 v1, 0, v1
	v_mul_f32_e32 v1, 0x3e000000, v1
	v_fmac_f32_e32 v24, v228, v1
	v_max_f32_e32 v1, v4, v4
	v_max_f32_e32 v1, 0, v1
	v_mul_f32_e32 v1, 0x3e000000, v1
	v_fmac_f32_e32 v0, v236, v1
	v_max_f32_e32 v1, v12, v12
	v_max_f32_e32 v1, 0, v1
	v_mul_f32_e32 v1, 0x3e000000, v1
	v_fmac_f32_e32 v8, v244, v1
	v_max_f32_e32 v1, v21, v21
	v_max_f32_e32 v1, 0, v1
	v_mul_f32_e32 v1, 0x3e000000, v1
	v_fmac_f32_e32 v16, v221, v1
	v_max_f32_e32 v1, v29, v29
	v_max_f32_e32 v1, 0, v1
	v_mul_f32_e32 v1, 0x3e000000, v1
	v_fmac_f32_e32 v24, v229, v1
	v_max_f32_e32 v1, v5, v5
	v_max_f32_e32 v1, 0, v1
	v_mul_f32_e32 v1, 0x3e000000, v1
	v_fmac_f32_e32 v0, v237, v1
	v_max_f32_e32 v1, v13, v13
	v_max_f32_e32 v1, 0, v1
	v_mul_f32_e32 v1, 0x3e000000, v1
	v_fmac_f32_e32 v8, v245, v1
	v_max_f32_e32 v1, v22, v22
	v_max_f32_e32 v1, 0, v1
	v_mul_f32_e32 v1, 0x3e000000, v1
	v_fmac_f32_e32 v16, v222, v1
	v_max_f32_e32 v1, v30, v30
	v_max_f32_e32 v1, 0, v1
	v_mul_f32_e32 v1, 0x3e000000, v1
	v_fmac_f32_e32 v24, v230, v1
	v_max_f32_e32 v1, v6, v6
	v_max_f32_e32 v1, 0, v1
	v_mul_f32_e32 v1, 0x3e000000, v1
	v_fmac_f32_e32 v0, v238, v1
	v_max_f32_e32 v1, v14, v14
	v_max_f32_e32 v1, 0, v1
	v_mul_f32_e32 v1, 0x3e000000, v1
	v_fmac_f32_e32 v8, v246, v1
	v_max_f32_e32 v1, v23, v23
	v_max_f32_e32 v1, 0, v1
	v_mul_f32_e32 v1, 0x3e000000, v1
	v_fmac_f32_e32 v16, v223, v1
	v_max_f32_e32 v1, v31, v31
	v_max_f32_e32 v1, 0, v1
	v_mul_f32_e32 v1, 0x3e000000, v1
	v_fmac_f32_e32 v24, v231, v1
	v_max_f32_e32 v1, v7, v7
	v_max_f32_e32 v1, 0, v1
	v_mul_f32_e32 v1, 0x3e000000, v1
	v_fmac_f32_e32 v0, v239, v1
	v_max_f32_e32 v1, v15, v15
	v_max_f32_e32 v1, 0, v1
	v_mul_f32_e32 v1, 0x3e000000, v1
	v_fmac_f32_e32 v8, v247, v1
	v_cndmask_b32_e64 v1, v16, v24, s[40:41]
	v_cndmask_b32_e64 v2, v0, v8, s[40:41]
	ds_bpermute_b32 v1, v97, v1
	ds_bpermute_b32 v2, v97, v2
	v_cndmask_b32_e64 v3, v24, v16, s[40:41]
	v_cndmask_b32_e64 v0, v8, v0, s[40:41]
	s_waitcnt lgkmcnt(1)
; #define LAS __attribute__((address_space(3)))
; __device__ __forceinline__ void idx_unit(bf16* QB, float* SC, int* SEL, const float* qg, const float* kg, int b, int tp, LAS unsigned char* wl, int lane, bool do_norm) {
;     ...
;             for (int tt = 0; tt < 2; ++tt) {
;                 f32x16 acc0, acc1;
; #pragma unroll
;                 for (int r = 0; r < 16; ++r) { acc0[r] = 0.f; acc1[r] = 0.f; }
; #pragma unroll
;                 for (int ks = 0; ks < 4; ++ks) { const bf16x8 bfr = *(const LAS bf16x8*)(fsrc + tt * 32 * 144 + 32 * ks);
;                     acc0 = __builtin_amdgcn_mfma_f32_32x32x16_bf16(af[0][ks], bfr, acc0, 0, 0, 0); acc1 = __builtin_amdgcn_mfma_f32_32x32x16_bf16(af[1][ks], bfr, acc1, 0, 0, 0); }
;                 float pa = 0.f, pb = 0.f, pc = 0.f, pd = 0.f;
; #pragma unroll
;                 for (int r = 0; r < 8; ++r) { pa += w[0][r] * (__builtin_fmaxf(acc0[r], 0.f) * 0.125f); pb += w[1][r] * (__builtin_fmaxf(acc0[8 + r], 0.f) * 0.125f);
;                                               pc += w[2][r] * (__builtin_fmaxf(acc1[r], 0.f) * 0.125f); pd += w[3][r] * (__builtin_fmaxf(acc1[8 + r], 0.f) * 0.125f); }
;                 const float snd0 = hi ? pa : pb, snd1 = hi ? pc : pd; const float rcv0 = __shfl_xor(snd0, 32), rcv1 = __shfl_xor(snd1, 32);
;                 scw0[s0 + 32 * tt] = (hi ? pb : pa) + rcv0;
;                 scw1[s0 + 32 * tt] = (hi ? pd : pc) + rcv1;
;             }
	v_add_f32_e32 v1, v3, v1
	s_waitcnt lgkmcnt(0)
	v_add_f32_e32 v0, v0, v2
	global_store_dword v[134:135], v1, off
	global_store_dword v[136:137], v0, off
	v_mfma_f32_32x32x16_bf16 v[16:31], v[40:43], v[154:157], 0
	v_mfma_f32_32x32x16_bf16 v[0:15], v[56:59], v[154:157], 0
	v_mfma_f32_32x32x16_bf16 v[0:15], v[48:51], v[158:161], v[0:15]
	v_mfma_f32_32x32x16_bf16 v[16:31], v[32:35], v[158:161], v[16:31]
	v_mfma_f32_32x32x16_bf16 v[0:15], v[52:55], v[162:165], v[0:15]
	v_mfma_f32_32x32x16_bf16 v[16:31], v[36:39], v[162:165], v[16:31]
	v_mfma_f32_32x32x16_bf16 v[0:15], v[60:63], v[166:169], v[0:15]
	v_mfma_f32_32x32x16_bf16 v[16:31], v[44:47], v[166:169], v[16:31]
	s_nop 10
	v_max_f32_e32 v0, v0, v0
	v_max_f32_e32 v0, 0, v0
	v_max_f32_e32 v1, v1, v1
	v_mul_f32_e32 v0, 0x3e000000, v0
	v_max_f32_e32 v1, 0, v1
	v_fma_f32 v0, v232, v0, 0
	v_max_f32_e32 v8, v8, v8
	v_mul_f32_e32 v1, 0x3e000000, v1
	v_max_f32_e32 v8, 0, v8
	v_fmac_f32_e32 v0, v233, v1
	v_max_f32_e32 v1, v9, v9
	v_max_f32_e32 v16, v16, v16
	v_mul_f32_e32 v8, 0x3e000000, v8
	v_max_f32_e32 v1, 0, v1
	v_max_f32_e32 v16, 0, v16
	v_fma_f32 v8, v240, v8, 0
	v_max_f32_e32 v17, v17, v17
	v_mul_f32_e32 v1, 0x3e000000, v1
	v_mul_f32_e32 v16, 0x3e000000, v16
	v_max_f32_e32 v17, 0, v17
	v_fmac_f32_e32 v8, v241, v1
	v_max_f32_e32 v1, v18, v18
	v_fma_f32 v16, v131, v16, 0
	v_max_f32_e32 v24, v24, v24
	v_mul_f32_e32 v17, 0x3e000000, v17
	v_max_f32_e32 v1, 0, v1
	v_max_f32_e32 v24, 0, v24
	v_fmac_f32_e32 v16, v217, v17
	v_max_f32_e32 v17, v25, v25
	v_mul_f32_e32 v1, 0x3e000000, v1
	v_mul_f32_e32 v24, 0x3e000000, v24
	v_max_f32_e32 v17, 0, v17
	v_fmac_f32_e32 v16, v218, v1
	v_max_f32_e32 v1, v26, v26
	v_fma_f32 v24, v224, v24, 0
	v_mul_f32_e32 v17, 0x3e000000, v17
	v_max_f32_e32 v1, 0, v1
	v_fmac_f32_e32 v24, v225, v17
	v_mul_f32_e32 v1, 0x3e000000, v1
	v_fmac_f32_e32 v24, v226, v1
	v_max_f32_e32 v1, v2, v2
	v_max_f32_e32 v1, 0, v1
	v_mul_f32_e32 v1, 0x3e000000, v1
	v_fmac_f32_e32 v0, v234, v1
	v_max_f32_e32 v1, v10, v10
	v_max_f32_e32 v1, 0, v1
	v_mul_f32_e32 v1, 0x3e000000, v1
	v_fmac_f32_e32 v8, v242, v1
	v_max_f32_e32 v1, v19, v19
	v_max_f32_e32 v1, 0, v1
	v_mul_f32_e32 v1, 0x3e000000, v1
	v_fmac_f32_e32 v16, v219, v1
	v_max_f32_e32 v1, v27, v27
	v_max_f32_e32 v1, 0, v1
	v_mul_f32_e32 v1, 0x3e000000, v1
	v_fmac_f32_e32 v24, v227, v1
	v_max_f32_e32 v1, v3, v3
	v_max_f32_e32 v1, 0, v1
	v_mul_f32_e32 v1, 0x3e000000, v1
	v_fmac_f32_e32 v0, v235, v1
	v_max_f32_e32 v1, v11, v11
	v_max_f32_e32 v1, 0, v1
	v_mul_f32_e32 v1, 0x3e000000, v1
	v_fmac_f32_e32 v8, v243, v1
	v_max_f32_e32 v1, v20, v20
	v_max_f32_e32 v1, 0, v1
	v_mul_f32_e32 v1, 0x3e000000, v1
	v_fmac_f32_e32 v16, v220, v1
	v_max_f32_e32 v1, v28, v28
	v_max_f32_e32 v1, 0, v1
	v_mul_f32_e32 v1, 0x3e000000, v1
	v_fmac_f32_e32 v24, v228, v1
	v_max_f32_e32 v1, v4, v4
	v_max_f32_e32 v1, 0, v1
	v_mul_f32_e32 v1, 0x3e000000, v1
	v_fmac_f32_e32 v0, v236, v1
	v_max_f32_e32 v1, v12, v12
	v_max_f32_e32 v1, 0, v1
	v_mul_f32_e32 v1, 0x3e000000, v1
	v_fmac_f32_e32 v8, v244, v1
	v_max_f32_e32 v1, v21, v21
	v_max_f32_e32 v1, 0, v1
	v_mul_f32_e32 v1, 0x3e000000, v1
	v_fmac_f32_e32 v16, v221, v1
	v_max_f32_e32 v1, v29, v29
	v_max_f32_e32 v1, 0, v1
	v_mul_f32_e32 v1, 0x3e000000, v1
	v_fmac_f32_e32 v24, v229, v1
	v_max_f32_e32 v1, v5, v5
	v_max_f32_e32 v1, 0, v1
	v_mul_f32_e32 v1, 0x3e000000, v1
	v_fmac_f32_e32 v0, v237, v1
	v_max_f32_e32 v1, v13, v13
	v_max_f32_e32 v1, 0, v1
	v_mul_f32_e32 v1, 0x3e000000, v1
	v_fmac_f32_e32 v8, v245, v1
	v_max_f32_e32 v1, v22, v22
	v_max_f32_e32 v1, 0, v1
	v_mul_f32_e32 v1, 0x3e000000, v1
	v_fmac_f32_e32 v16, v222, v1
	v_max_f32_e32 v1, v30, v30
	v_max_f32_e32 v1, 0, v1
	v_mul_f32_e32 v1, 0x3e000000, v1
	v_fmac_f32_e32 v24, v230, v1
	v_max_f32_e32 v1, v6, v6
	v_max_f32_e32 v1, 0, v1
	v_mul_f32_e32 v1, 0x3e000000, v1
	v_fmac_f32_e32 v0, v238, v1
	v_max_f32_e32 v1, v14, v14
	v_max_f32_e32 v1, 0, v1
	v_mul_f32_e32 v1, 0x3e000000, v1
	v_fmac_f32_e32 v8, v246, v1
	v_max_f32_e32 v1, v23, v23
	v_max_f32_e32 v1, 0, v1
	v_mul_f32_e32 v1, 0x3e000000, v1
	v_fmac_f32_e32 v16, v223, v1
	v_max_f32_e32 v1, v31, v31
	v_max_f32_e32 v1, 0, v1
	v_mul_f32_e32 v1, 0x3e000000, v1
	v_fmac_f32_e32 v24, v231, v1
	v_max_f32_e32 v1, v7, v7
	v_max_f32_e32 v1, 0, v1
	v_mul_f32_e32 v1, 0x3e000000, v1
	v_fmac_f32_e32 v0, v239, v1
	v_max_f32_e32 v1, v15, v15
	v_max_f32_e32 v1, 0, v1
	v_mul_f32_e32 v1, 0x3e000000, v1
	v_fmac_f32_e32 v8, v247, v1
	v_cndmask_b32_e64 v1, v16, v24, s[40:41]
	v_cndmask_b32_e64 v2, v0, v8, s[40:41]
	ds_bpermute_b32 v1, v97, v1
	ds_bpermute_b32 v2, v97, v2
	v_cndmask_b32_e64 v3, v24, v16, s[40:41]
	v_cndmask_b32_e64 v0, v8, v0, s[40:41]
	s_waitcnt lgkmcnt(1)
	v_add_f32_e32 v1, v3, v1
	s_waitcnt lgkmcnt(0)
	v_add_f32_e32 v0, v0, v2
	global_store_dword v[134:135], v1, off offset:128
	global_store_dword v[136:137], v0, off offset:128
	s_waitcnt lgkmcnt(0)
	v_lshl_add_u64 v[134:135], v[134:135], 0, s[0:1]
	s_mov_b32 s0, s3
	s_cbranch_vccnz .LBB0_243
; __device__ __forceinline__ unsigned fkey(float f) { const unsigned u = __builtin_bit_cast(unsigned, f); return (u & 0x80000000u) ? ~u : (u | 0x80000000u); }
; __device__ __forceinline__ int mbcnt(unsigned long long m) { return __builtin_amdgcn_mbcnt_hi((unsigned)(m >> 32), __builtin_amdgcn_mbcnt_lo((unsigned)m, 0u)); }
; __device__ __forceinline__ void select_query(const float* sc, int* sel, int ce, int lane) {
;     const int nreg = ce >> 6;
;     unsigned key[64];
;     {
;         float raw[64];
; #pragma unroll
;         for (int g = 0; g < 8; ++g) {
;             if (8 * g < nreg) {
; #pragma unroll
;                 for (int j = 8 * g; j < 8 * g + 8; ++j) raw[j] = sc[lane + 64 * j];
;             } else {
; #pragma unroll
;                 for (int j = 8 * g; j < 8 * g + 8; ++j) raw[j] = 0.f;
;             }
;         }
; #pragma unroll
;         for (int j = 0; j < 64; ++j) key[j] = (j < nreg) ? fkey(raw[j]) : 0u;
;     ...
;         for (int j = 0; j < 8; ++j) { if (key[8 * g + j] > thr) sel[pos + mbcnt(m[j])] = lane + 64 * (8 * g + j); pos += __builtin_popcountll(m[j]); }
	v_add_u32_e32 v138, 0x180, v96
	v_add_u32_e32 v139, 0x1c0, v96
	v_add_u32_e32 v140, 0x200, v96
	v_add_u32_e32 v141, 0x240, v96
	v_add_u32_e32 v142, 0x280, v96
	v_add_u32_e32 v143, 0x2c0, v96
	v_add_u32_e32 v144, 0x300, v96
	v_add_u32_e32 v145, 0x340, v96
	v_add_u32_e32 v146, 0x380, v96
	v_add_u32_e32 v147, 0x3c0, v96
	v_add_u32_e32 v148, 0x400, v96
	v_add_u32_e32 v149, 0x440, v96
	v_add_u32_e32 v150, 0x480, v96
	v_add_u32_e32 v151, 0x4c0, v96
	v_add_u32_e32 v152, 0x500, v96
	v_add_u32_e32 v153, 0x540, v96
	v_add_u32_e32 v154, 0x580, v96
	v_add_u32_e32 v155, 0x5c0, v96
	v_add_u32_e32 v156, 0x600, v96
	v_add_u32_e32 v157, 0x640, v96
	v_add_u32_e32 v158, 0x680, v96
	v_add_u32_e32 v159, 0x6c0, v96
	v_add_u32_e32 v160, 0x700, v96
	v_add_u32_e32 v161, 0x740, v96
	v_add_u32_e32 v162, 0x780, v96
	v_add_u32_e32 v163, 0x7c0, v96
	v_add_u32_e32 v164, 0x800, v96
	v_add_u32_e32 v165, 0x840, v96
	v_add_u32_e32 v166, 0x880, v96
	v_add_u32_e32 v167, 0x8c0, v96
	v_add_u32_e32 v168, 0x900, v96
	v_add_u32_e32 v169, 0x940, v96
	s_cmpk_gt_u32 s6, 0x23f
	s_cselect_b64 s[84:85], -1, 0
	s_cmpk_gt_u32 s6, 0x43f
	s_cselect_b64 s[86:87], -1, 0
	s_cmpk_gt_u32 s6, 0x63f
	s_cselect_b64 s[88:89], -1, 0
	s_cmpk_gt_u32 s6, 0x83f
	s_cselect_b64 s[90:91], -1, 0
	s_cmpk_gt_u32 s6, 0xa3f
	s_cselect_b64 s[92:93], -1, 0
	s_cmpk_gt_u32 s6, 0xc3f
	s_cselect_b64 s[94:95], -1, 0
	s_cmpk_gt_u32 s6, 0xe3f
	s_cselect_b64 s[96:97], -1, 0
	s_cmpk_gt_u32 s6, 0x17f
	s_cselect_b64 s[0:1], -1, 0
	v_writelane_b32 v254, s0, 7
	s_cmpk_gt_u32 s6, 0x1bf
	s_nop 0
	v_writelane_b32 v254, s1, 8
	s_cselect_b64 s[0:1], -1, 0
	v_writelane_b32 v254, s0, 9
	s_cmpk_gt_u32 s6, 0x1ff
	s_waitcnt vmcnt(0)
; __device__ __forceinline__ unsigned fkey(float f) { const unsigned u = __builtin_bit_cast(unsigned, f); return (u & 0x80000000u) ? ~u : (u | 0x80000000u); }
; __device__ __forceinline__ void select_query(const float* sc, int* sel, int ce, int lane) {
;     const int nreg = ce >> 6;
;     unsigned key[64];
;     {
;         float raw[64];
; #pragma unroll
;         for (int g = 0; g < 8; ++g) {
;             if (8 * g < nreg) {
; #pragma unroll
;                 for (int j = 8 * g; j < 8 * g + 8; ++j) raw[j] = sc[lane + 64 * j];
;             } else {
; #pragma unroll
;                 for (int j = 8 * g; j < 8 * g + 8; ++j) raw[j] = 0.f;
;             }
;         }
; #pragma unroll
;         for (int j = 0; j < 64; ++j) key[j] = (j < nreg) ? fkey(raw[j]) : 0u;
	s_mov_b32 s3, 0
	v_writelane_b32 v254, s1, 10
	s_cselect_b64 s[0:1], -1, 0
	v_writelane_b32 v254, s0, 11
	s_cmpk_gt_u32 s6, 0x27f
	s_nop 0
	v_writelane_b32 v254, s1, 12
	s_cselect_b64 s[0:1], -1, 0
	v_writelane_b32 v254, s0, 13
	s_cmpk_gt_u32 s6, 0x2bf
	s_nop 0
	v_writelane_b32 v254, s1, 14
	s_cselect_b64 s[0:1], -1, 0
	v_writelane_b32 v254, s0, 15
	s_cmpk_gt_u32 s6, 0x2ff
	s_nop 0
	v_writelane_b32 v254, s1, 16
	s_cselect_b64 s[0:1], -1, 0
	v_writelane_b32 v254, s0, 17
	s_cmpk_gt_u32 s6, 0x33f
	s_nop 0
	v_writelane_b32 v254, s1, 18
	s_cselect_b64 s[0:1], -1, 0
	v_writelane_b32 v254, s0, 19
	s_cmpk_gt_u32 s6, 0x37f
	s_nop 0
	v_writelane_b32 v254, s1, 20
	s_cselect_b64 s[0:1], -1, 0
	v_writelane_b32 v254, s0, 21
	s_cmpk_gt_u32 s6, 0x3bf
	s_nop 0
	v_writelane_b32 v254, s1, 22
	s_cselect_b64 s[0:1], -1, 0
	v_writelane_b32 v254, s0, 23
	s_cmpk_gt_u32 s6, 0x3ff
	s_nop 0
	v_writelane_b32 v254, s1, 24
	s_cselect_b64 s[0:1], -1, 0
	v_writelane_b32 v254, s0, 25
	s_cmpk_gt_u32 s6, 0x47f
	s_nop 0
	v_writelane_b32 v254, s1, 26
	s_cselect_b64 s[0:1], -1, 0
	v_writelane_b32 v254, s0, 27
	s_cmpk_gt_u32 s6, 0x4bf
	s_nop 0
	v_writelane_b32 v254, s1, 28
	s_cselect_b64 s[0:1], -1, 0
	v_writelane_b32 v254, s0, 29
	s_cmpk_gt_u32 s6, 0x4ff
	s_nop 0
	v_writelane_b32 v254, s1, 30
	s_cselect_b64 s[0:1], -1, 0
	v_writelane_b32 v254, s0, 31
	s_cmpk_gt_u32 s6, 0x53f
	s_nop 0
	v_writelane_b32 v254, s1, 32
	s_cselect_b64 s[0:1], -1, 0
	v_writelane_b32 v254, s0, 33
	s_cmpk_gt_u32 s6, 0x57f
	s_nop 0
	v_writelane_b32 v254, s1, 34
	s_cselect_b64 s[0:1], -1, 0
	v_writelane_b32 v254, s0, 35
	s_cmpk_gt_u32 s6, 0x5bf
	s_nop 0
	v_writelane_b32 v254, s1, 36
	s_cselect_b64 s[0:1], -1, 0
	v_writelane_b32 v254, s0, 37
	s_cmpk_gt_u32 s6, 0x5ff
	s_nop 0
	v_writelane_b32 v254, s1, 38
	s_cselect_b64 s[0:1], -1, 0
	v_writelane_b32 v254, s0, 39
	s_cmpk_gt_u32 s6, 0x67f
	s_nop 0
	v_writelane_b32 v254, s1, 40
	s_cselect_b64 s[0:1], -1, 0
	v_writelane_b32 v254, s0, 41
	s_cmpk_gt_u32 s6, 0x6bf
	s_nop 0
	v_writelane_b32 v254, s1, 42
	s_cselect_b64 s[0:1], -1, 0
	v_writelane_b32 v254, s0, 43
	s_cmpk_gt_u32 s6, 0x6ff
	s_nop 0
	v_writelane_b32 v254, s1, 44
	s_cselect_b64 s[0:1], -1, 0
	v_writelane_b32 v254, s0, 45
	s_cmpk_gt_u32 s6, 0x73f
	s_nop 0
	v_writelane_b32 v254, s1, 46
	s_cselect_b64 s[0:1], -1, 0
	v_writelane_b32 v254, s0, 47
	s_cmpk_gt_u32 s6, 0x77f
	s_nop 0
	v_writelane_b32 v254, s1, 48
	s_cselect_b64 s[0:1], -1, 0
	v_writelane_b32 v254, s0, 49
	s_cmpk_gt_u32 s6, 0x7bf
	s_nop 0
	v_writelane_b32 v254, s1, 50
	s_cselect_b64 s[0:1], -1, 0
	v_writelane_b32 v254, s0, 51
	s_cmpk_gt_u32 s6, 0x7ff
	s_nop 0
	v_writelane_b32 v254, s1, 52
	s_cselect_b64 s[0:1], -1, 0
	v_writelane_b32 v254, s0, 53
	s_cmpk_gt_u32 s6, 0x87f
	s_nop 0
	v_writelane_b32 v254, s1, 54
	s_cselect_b64 s[0:1], -1, 0
	v_writelane_b32 v254, s0, 55
	s_cmpk_gt_u32 s6, 0x8bf
	s_nop 0
	v_writelane_b32 v254, s1, 56
	s_cselect_b64 s[0:1], -1, 0
	v_writelane_b32 v254, s0, 57
	s_cmpk_gt_u32 s6, 0x8ff
	s_nop 0
	v_writelane_b32 v254, s1, 58
	s_cselect_b64 s[0:1], -1, 0
	v_writelane_b32 v254, s0, 59
	s_cmpk_gt_u32 s6, 0x93f
	s_nop 0
	v_writelane_b32 v254, s1, 60
	s_cselect_b64 s[0:1], -1, 0
	v_writelane_b32 v254, s0, 61
	s_cmpk_gt_u32 s6, 0x97f
	s_nop 0
	v_writelane_b32 v254, s1, 62
	s_cselect_b64 s[0:1], -1, 0
	v_writelane_b32 v254, s0, 63
	s_cmpk_gt_u32 s6, 0x9bf
	s_nop 0
	v_writelane_b32 v250, s1, 0
	s_cselect_b64 s[0:1], -1, 0
	v_writelane_b32 v250, s0, 1
	s_cmpk_gt_u32 s6, 0x9ff
	s_nop 0
	v_writelane_b32 v250, s1, 2
	s_cselect_b64 s[0:1], -1, 0
	v_writelane_b32 v250, s0, 3
	s_cmpk_gt_u32 s6, 0xa7f
	s_nop 0
	v_writelane_b32 v250, s1, 4
	s_cselect_b64 s[0:1], -1, 0
	v_writelane_b32 v250, s0, 5
	s_cmpk_gt_u32 s6, 0xabf
	s_nop 0
	v_writelane_b32 v250, s1, 6
	s_cselect_b64 s[0:1], -1, 0
	v_writelane_b32 v250, s0, 7
	s_cmpk_gt_u32 s6, 0xaff
	s_nop 0
	v_writelane_b32 v250, s1, 8
	s_cselect_b64 s[0:1], -1, 0
	v_writelane_b32 v250, s0, 9
	s_cmpk_gt_u32 s6, 0xb3f
	s_nop 0
	v_writelane_b32 v250, s1, 10
	s_cselect_b64 s[0:1], -1, 0
	v_writelane_b32 v250, s0, 11
	s_cmpk_gt_u32 s6, 0xb7f
	s_nop 0
	v_writelane_b32 v250, s1, 12
	s_cselect_b64 s[0:1], -1, 0
	v_writelane_b32 v250, s0, 13
	s_cmpk_gt_u32 s6, 0xbbf
	s_nop 0
	v_writelane_b32 v250, s1, 14
	s_cselect_b64 s[0:1], -1, 0
	v_writelane_b32 v250, s0, 15
	s_cmpk_gt_u32 s6, 0xbff
	s_nop 0
	v_writelane_b32 v250, s1, 16
	s_cselect_b64 s[0:1], -1, 0
	v_writelane_b32 v250, s0, 17
	s_cmpk_gt_u32 s6, 0xc7f
	s_nop 0
	v_writelane_b32 v250, s1, 18
	s_cselect_b64 s[0:1], -1, 0
	v_writelane_b32 v250, s0, 19
	s_cmpk_gt_u32 s6, 0xcbf
	s_nop 0
	v_writelane_b32 v250, s1, 20
	s_cselect_b64 s[0:1], -1, 0
	v_writelane_b32 v250, s0, 21
	s_cmpk_gt_u32 s6, 0xcff
	s_nop 0
	v_writelane_b32 v250, s1, 22
	s_cselect_b64 s[0:1], -1, 0
	v_writelane_b32 v250, s0, 23
	s_cmpk_gt_u32 s6, 0xd3f
	s_nop 0
	v_writelane_b32 v250, s1, 24
	s_cselect_b64 s[0:1], -1, 0
	v_writelane_b32 v250, s0, 25
	s_cmpk_gt_u32 s6, 0xd7f
	s_nop 0
	v_writelane_b32 v250, s1, 26
	s_cselect_b64 s[0:1], -1, 0
	v_writelane_b32 v250, s0, 27
	s_cmpk_gt_u32 s6, 0xdbf
	s_nop 0
	v_writelane_b32 v250, s1, 28
	s_cselect_b64 s[0:1], -1, 0
	v_writelane_b32 v250, s0, 29
	s_cmpk_gt_u32 s6, 0xdff
	s_nop 0
	v_writelane_b32 v250, s1, 30
	s_cselect_b64 s[0:1], -1, 0
	s_cmpk_gt_u32 s6, 0xe7f
	s_cselect_b64 s[36:37], -1, 0
	s_cmpk_gt_u32 s6, 0xebf
	s_cselect_b64 s[38:39], -1, 0
	s_cmpk_gt_u32 s6, 0xeff
	s_cselect_b64 s[42:43], -1, 0
	s_cmpk_gt_u32 s6, 0xf3f
	s_cselect_b64 s[44:45], -1, 0
	s_cmpk_gt_u32 s6, 0xf7f
	s_cselect_b64 s[46:47], -1, 0
	s_cmpk_gt_u32 s6, 0xfbf
	s_cselect_b64 s[48:49], -1, 0
	s_cmpk_gt_u32 s6, 0xfff
	v_writelane_b32 v250, s0, 31
	s_cselect_b64 s[50:51], -1, 0
	s_nop 0
	v_writelane_b32 v250, s1, 32
	s_branch .LBB0_247

; __device__ __forceinline__ unsigned pk2(float lo, float hi) { return pg8::cvt_pk_bf16(lo, hi); }
; __device__ __forceinline__ void dsa_unit(const bf16* QB, const int* SEL, bf16* AO, int b, int kvh, int t, LAS unsigned char* wl, int lane) {
;     ...
;         for (int kb = 0; kb < 8; ++kb) { const float e = __builtin_amdgcn_exp2f(lg[kb][g] - m); lg[kb][g] = e; s += e; }
;         s += __shfl_xor(s, 1); s += __shfl_xor(s, 2); s += __shfl_xor(s, 4); s += __shfl_xor(s, 8); s += __shfl_xor(s, 16);
;         const float inv = 1.0f / s;
; #pragma unroll
;         for (int kb = 0; kb < 8; ++kb) if ((kb >> 2) == hi) pT[g * 256 + 32 * kb + n] = (bf16)(pk2(lg[kb][g] * inv, 0.f) & 0xffffu);
;     ...
;     bf16* op = AO + row * D + (kvh * 4) * 128 + 16 * kq + l15;
; #pragma unroll
;     for (int i = 0; i < 2; ++i)
; #pragma unroll
;         for (int g = 0; g < 4; ++g) {
;             const float v = (kq == 0) ? o[4 * i][g] : (kq == 1) ? o[4 * i + 1][g] : (kq == 2) ? o[4 * i + 2][g] : o[4 * i + 3][g];
;             op[g * 128 + 64 * i] = (bf16)(pk2(v, 0.f) & 0xffffu);
;         }
.Ldsa_exit:
	s_waitcnt vmcnt(0)
	v_xor_b32_e32 v178, 32, v206
	v_lshlrev_b32_e32 v178, 2, v178
	ds_bpermute_b32 v179, v178, v173
	s_waitcnt lgkmcnt(0)
	v_add_f32_e32 v173, v173, v179
	v_rcp_f32_e32 v173, v173
	s_nop 0
	v_and_b32_e32 v178, 31, v206
	v_lshlrev_b32_e32 v178, 2, v178
	s_lshl_b32 s24, s0, 7
	s_add_u32 s24, s24, 0x1b000
	v_add_u32_e32 v178, s24, v178
	ds_write_b32 v178, v173
	v_lshl_add_u32 v179, v175, 1, s24
	s_waitcnt lgkmcnt(0)
	ds_read_b128 v[112:115], v179 offset:0
	ds_read_b128 v[116:119], v179 offset:32
	ds_read_b128 v[120:123], v179 offset:64
	ds_read_b128 v[124:127], v179 offset:96
	v_and_b32_e32 v178, 31, v206
	v_lshlrev_b32_e32 v178, 1, v178
	v_mul_u32_u24_e32 v179, 0x88, v175
	v_add3_u32 v178, v178, v179, s45
	v_lshrrev_b32_e32 v179, 4, v206
	v_mul_u32_u24_e32 v182, 0x110, v179
	v_and_b32_e32 v172, 15, v206
	v_lshl_add_u32 v182, v172, 4, v182
	v_add_u32_e32 v174, s45, v182
	s_add_u32 s24, s44, s7
	s_add_u32 s24, s24, s4
	s_lshr_b32 s25, s24, 20
	s_lshl_b32 s24, s24, 12
	s_add_u32 s24, s24, s67
	s_addc_u32 s25, s25, s85
	s_lshl_b32 s26, s5, 10
	s_add_u32 s24, s24, s26
	s_addc_u32 s25, s25, 0
	v_lshlrev_b32_e32 v179, 8, v179
	v_lshl_add_u32 v182, v172, 4, v179
	v_lshl_add_u64 v[144:145], s[24:25], 0, v[182:183]
	s_movk_i32 s26, 0x1000
	s_mov_b32 s27, 0
	s_waitcnt lgkmcnt(0)
	v_pk_mul_f32 v[0:1], v[0:1], v[112:113]
	v_pk_mul_f32 v[2:3], v[2:3], v[114:115]
	v_pk_mul_f32 v[4:5], v[4:5], v[116:117]
	v_pk_mul_f32 v[6:7], v[6:7], v[118:119]
	v_pk_mul_f32 v[8:9], v[8:9], v[120:121]
	v_pk_mul_f32 v[10:11], v[10:11], v[122:123]
	v_pk_mul_f32 v[12:13], v[12:13], v[124:125]
	v_pk_mul_f32 v[14:15], v[14:15], v[126:127]
	v_pk_mul_f32 v[16:17], v[16:17], v[112:113]
	v_pk_mul_f32 v[18:19], v[18:19], v[114:115]
	v_pk_mul_f32 v[20:21], v[20:21], v[116:117]
	v_pk_mul_f32 v[22:23], v[22:23], v[118:119]
	v_pk_mul_f32 v[24:25], v[24:25], v[120:121]
	v_pk_mul_f32 v[26:27], v[26:27], v[122:123]
	v_pk_mul_f32 v[28:29], v[28:29], v[124:125]
	v_pk_mul_f32 v[30:31], v[30:31], v[126:127]
	v_pk_mul_f32 v[32:33], v[32:33], v[112:113]
	v_pk_mul_f32 v[34:35], v[34:35], v[114:115]
	v_pk_mul_f32 v[36:37], v[36:37], v[116:117]
	v_pk_mul_f32 v[38:39], v[38:39], v[118:119]
	v_pk_mul_f32 v[40:41], v[40:41], v[120:121]
	v_pk_mul_f32 v[42:43], v[42:43], v[122:123]
	v_pk_mul_f32 v[44:45], v[44:45], v[124:125]
	v_pk_mul_f32 v[46:47], v[46:47], v[126:127]
	v_pk_mul_f32 v[48:49], v[48:49], v[112:113]
	v_pk_mul_f32 v[50:51], v[50:51], v[114:115]
	v_pk_mul_f32 v[52:53], v[52:53], v[116:117]
	v_pk_mul_f32 v[54:55], v[54:55], v[118:119]
	v_pk_mul_f32 v[56:57], v[56:57], v[120:121]
	v_pk_mul_f32 v[58:59], v[58:59], v[122:123]
	v_pk_mul_f32 v[60:61], v[60:61], v[124:125]
	v_pk_mul_f32 v[62:63], v[62:63], v[126:127]
	v_cvt_pk_bf16_f32 v64, v0, v1
	v_cvt_pk_bf16_f32 v65, v2, v3
	v_cvt_pk_bf16_f32 v66, v4, v5
	v_cvt_pk_bf16_f32 v67, v6, v7
	v_cvt_pk_bf16_f32 v68, v8, v9
	v_cvt_pk_bf16_f32 v69, v10, v11
	v_cvt_pk_bf16_f32 v70, v12, v13
	v_cvt_pk_bf16_f32 v71, v14, v15
	ds_write_b16 v178, v64 offset:0
	ds_write_b16_d16_hi v178, v64 offset:272
	ds_write_b16 v178, v65 offset:544
	ds_write_b16_d16_hi v178, v65 offset:816
	ds_write_b16 v178, v66 offset:2176
	ds_write_b16_d16_hi v178, v66 offset:2448
	ds_write_b16 v178, v67 offset:2720
	ds_write_b16_d16_hi v178, v67 offset:2992
	ds_write_b16 v178, v68 offset:4352
	ds_write_b16_d16_hi v178, v68 offset:4624
	ds_write_b16 v178, v69 offset:4896
	ds_write_b16_d16_hi v178, v69 offset:5168
	ds_write_b16 v178, v70 offset:6528
	ds_write_b16_d16_hi v178, v70 offset:6800
	ds_write_b16 v178, v71 offset:7072
	ds_write_b16_d16_hi v178, v71 offset:7344
	v_cvt_pk_bf16_f32 v72, v16, v17
	v_cvt_pk_bf16_f32 v73, v18, v19
	v_cvt_pk_bf16_f32 v74, v20, v21
	v_cvt_pk_bf16_f32 v75, v22, v23
	v_cvt_pk_bf16_f32 v76, v24, v25
	v_cvt_pk_bf16_f32 v77, v26, v27
	v_cvt_pk_bf16_f32 v78, v28, v29
	v_cvt_pk_bf16_f32 v79, v30, v31
	ds_write_b16 v178, v72 offset:64
	ds_write_b16_d16_hi v178, v72 offset:336
	ds_write_b16 v178, v73 offset:608
	ds_write_b16_d16_hi v178, v73 offset:880
	ds_write_b16 v178, v74 offset:2240
	ds_write_b16_d16_hi v178, v74 offset:2512
	ds_write_b16 v178, v75 offset:2784
	ds_write_b16_d16_hi v178, v75 offset:3056
	ds_write_b16 v178, v76 offset:4416
	ds_write_b16_d16_hi v178, v76 offset:4688
	ds_write_b16 v178, v77 offset:4960
	ds_write_b16_d16_hi v178, v77 offset:5232
	ds_write_b16 v178, v78 offset:6592
	ds_write_b16_d16_hi v178, v78 offset:6864
	ds_write_b16 v178, v79 offset:7136
	ds_write_b16_d16_hi v178, v79 offset:7408
	v_cvt_pk_bf16_f32 v128, v32, v33
	v_cvt_pk_bf16_f32 v129, v34, v35
	v_cvt_pk_bf16_f32 v130, v36, v37
	v_cvt_pk_bf16_f32 v131, v38, v39
	v_cvt_pk_bf16_f32 v132, v40, v41
	v_cvt_pk_bf16_f32 v133, v42, v43
	v_cvt_pk_bf16_f32 v134, v44, v45
	v_cvt_pk_bf16_f32 v135, v46, v47
	ds_write_b16 v178, v128 offset:128
	ds_write_b16_d16_hi v178, v128 offset:400
	ds_write_b16 v178, v129 offset:672
	ds_write_b16_d16_hi v178, v129 offset:944
	ds_write_b16 v178, v130 offset:2304
	ds_write_b16_d16_hi v178, v130 offset:2576
	ds_write_b16 v178, v131 offset:2848
	ds_write_b16_d16_hi v178, v131 offset:3120
	ds_write_b16 v178, v132 offset:4480
	ds_write_b16_d16_hi v178, v132 offset:4752
	ds_write_b16 v178, v133 offset:5024
	ds_write_b16_d16_hi v178, v133 offset:5296
	ds_write_b16 v178, v134 offset:6656
	ds_write_b16_d16_hi v178, v134 offset:6928
	ds_write_b16 v178, v135 offset:7200
	ds_write_b16_d16_hi v178, v135 offset:7472
	v_cvt_pk_bf16_f32 v136, v48, v49
	v_cvt_pk_bf16_f32 v137, v50, v51
	v_cvt_pk_bf16_f32 v138, v52, v53
	v_cvt_pk_bf16_f32 v139, v54, v55
	v_cvt_pk_bf16_f32 v140, v56, v57
	v_cvt_pk_bf16_f32 v141, v58, v59
	v_cvt_pk_bf16_f32 v142, v60, v61
	v_cvt_pk_bf16_f32 v143, v62, v63
	ds_write_b16 v178, v136 offset:192
	ds_write_b16_d16_hi v178, v136 offset:464
	ds_write_b16 v178, v137 offset:736
	ds_write_b16_d16_hi v178, v137 offset:1008
	ds_write_b16 v178, v138 offset:2368
	ds_write_b16_d16_hi v178, v138 offset:2640
	ds_write_b16 v178, v139 offset:2912
	ds_write_b16_d16_hi v178, v139 offset:3184
	ds_write_b16 v178, v140 offset:4544
	ds_write_b16_d16_hi v178, v140 offset:4816
	ds_write_b16 v178, v141 offset:5088
	ds_write_b16_d16_hi v178, v141 offset:5360
	ds_write_b16 v178, v142 offset:6720
	ds_write_b16_d16_hi v178, v142 offset:6992
	ds_write_b16 v178, v143 offset:7264
	ds_write_b16_d16_hi v178, v143 offset:7536
	s_waitcnt lgkmcnt(0)
; __device__ __forceinline__ unsigned pk2(float lo, float hi) { return pg8::cvt_pk_bf16(lo, hi); }
; __device__ __forceinline__ void dsa_unit(const bf16* QB, const int* SEL, bf16* AO, int b, int kvh, int t, LAS unsigned char* wl, int lane) {
;     ...
;     bf16* op = AO + row * D + (kvh * 4) * 128 + 16 * kq + l15;
; #pragma unroll
;     for (int i = 0; i < 2; ++i)
; #pragma unroll
;         for (int g = 0; g < 4; ++g) {
;             const float v = (kq == 0) ? o[4 * i][g] : (kq == 1) ? o[4 * i + 1][g] : (kq == 2) ? o[4 * i + 2][g] : o[4 * i + 3][g];
;             op[g * 128 + 64 * i] = (bf16)(pk2(v, 0.f) & 0xffffu);
;         }
	ds_read_b128 v[80:83], v174 offset:0
	ds_read_b128 v[84:87], v174 offset:1088
	ds_read_b128 v[88:91], v174 offset:2176
	ds_read_b128 v[92:95], v174 offset:3264
	ds_read_b128 v[96:99], v174 offset:4352
	ds_read_b128 v[100:103], v174 offset:5440
	ds_read_b128 v[104:107], v174 offset:6528
	ds_read_b128 v[108:111], v174 offset:7616
	s_waitcnt lgkmcnt(7)
	global_store_dwordx4 v[144:145], v[80:83], off sc1
	v_lshl_add_u64 v[144:145], v[144:145], 0, s[26:27]
	s_waitcnt lgkmcnt(6)
	global_store_dwordx4 v[144:145], v[84:87], off sc1
	v_lshl_add_u64 v[144:145], v[144:145], 0, s[26:27]
	s_waitcnt lgkmcnt(5)
	global_store_dwordx4 v[144:145], v[88:91], off sc1
	v_lshl_add_u64 v[144:145], v[144:145], 0, s[26:27]
	s_waitcnt lgkmcnt(4)
	global_store_dwordx4 v[144:145], v[92:95], off sc1
	v_lshl_add_u64 v[144:145], v[144:145], 0, s[26:27]
	s_waitcnt lgkmcnt(3)
	global_store_dwordx4 v[144:145], v[96:99], off sc1
	v_lshl_add_u64 v[144:145], v[144:145], 0, s[26:27]
	s_waitcnt lgkmcnt(2)
	global_store_dwordx4 v[144:145], v[100:103], off sc1
	v_lshl_add_u64 v[144:145], v[144:145], 0, s[26:27]
	s_waitcnt lgkmcnt(1)
	global_store_dwordx4 v[144:145], v[104:107], off sc1
	v_lshl_add_u64 v[144:145], v[144:145], 0, s[26:27]
	s_waitcnt lgkmcnt(0)
	global_store_dwordx4 v[144:145], v[108:111], off sc1
	s_add_u32 s21, s21, 1
	s_cmp_lt_u32 s21, 2
	s_cbranch_scc1 .Ldsa_half
	s_add_u32 s3, s3, s2
	s_branch .Ldsa_unit
